# back-edge rotation (7.11) on both GEMM K-loops and the peeled first trip: counter/address bumps and the exit compare moved from after the loop-back barrier into the last MFMA block
# baseline (speedup 1.0000x reference)
; #define PG8_WAIT_V(n) asm volatile("s_waitcnt vmcnt(" #n ")" ::: "memory")
; template <class Epi, class Sched, bool ALIGN_EPI = false, bool SP2 = false>
; __device__ __forceinline__ void gemm_phase(PG8_LAS unsigned char* lds, const Gemm g, const Sched& S, const Epi& E) {
;     ...
;         const bool has_next = S.next(ui + 1, nxt);
;         const char* nA = has_next ? (const char*)g.A + (size_t)nxt.pm * tstep : cA; const char* nB = has_next ? (const char*)g.Bt + (size_t)nxt.pn * tstep : cB;
;         for (int t = 0; t < nt; t += 2) {
;             if constexpr (Epi::MID) { if (t == nt / 2) E.mid(acc, cur, wr, fr, lds); }
;             const bool last = (t == nt - 2);
;             const char* a1 = cA + (size_t)(t + 1) * kstep;
;             const char* a2 = last ? nA : cA + (size_t)(t + 2) * kstep; const char* b2 = last ? nB : cB + (size_t)(t + 2) * kstep;
;             const char* a3 = a2 + kstep; const char* b3 = b2 + kstep;
;             if (last && has_next) S.a_ready(nxt);
;             if constexpr (SP2) {
;             PG8_LDB(B0, 0, 0); PG8_LDB(B1, 0, 1); PG8_SCHED; PG8_LDA(At, 0, 0); PG8_STAGE(PG8_SA(1, 1), a1 + hstep, voffA);
;             PG8_WAIT_V(8); PG8_WAIT_L(0); PG8_BAR; PG8_MMA(0, 0, At, B0); PG8_MMA(0, 1, At, B1); PG8_BAR; PG8_SCHED;
;             if constexpr (Epi::XPF) {
;             const bool xsel = last && !has_next;
;             const char* xt = (const char*)E.x + ((size_t)cur.pm * BM * 1024 + (size_t)cur.pn * BM) * 4;
;             const unsigned vB[2] = {xsel ? voffX[0] : voffB[0], xsel ? voffX[1] : voffB[1]}, vA[2] = {xsel ? voffX[0] : voffA[0], xsel ? voffX[1] : voffA[1]};
;     ...
;             PG8_LDA(At, 0, 1); PG8_STAGE(PG8_SB(0, 0), xsel ? PG8_XR(0) : b2, vB); PG8_STAGE(PG8_SB(0, 1), xsel ? PG8_XR(1) : b2 + hstep, vB); PG8_STAGE(PG8_SA(0, 0), xsel ? PG8_XR(2) : a2, vA);
;             PG8_WAIT_V(8); PG8_WAIT_L(0); PG8_BAR; PG8_MMA(1, 0, At, B0); PG8_MMA(1, 1, At, B1); PG8_BAR; PG8_SCHED;
;             PG8_LDB(B0, 1, 0); PG8_LDB(B1, 1, 1); PG8_SCHED; PG8_LDA(At, 1, 0); PG8_STAGE(PG8_SA(0, 1), xsel ? PG8_XR(3) : a2 + hstep, vA);
;             PG8_WAIT_V(8); PG8_WAIT_L(0); PG8_BAR; PG8_MMA(0, 0, At, B0); PG8_MMA(0, 1, At, B1); PG8_BAR; PG8_SCHED;
;             PG8_LDA(At, 1, 1); PG8_STAGE(PG8_SB(1, 0), xsel ? PG8_XR(4) : b3, vB); PG8_STAGE(PG8_SB(1, 1), xsel ? PG8_XR(5) : b3 + hstep, vB); PG8_STAGE(PG8_SA(1, 0), xsel ? PG8_XR(6) : a3, vA);
.LBB0_132:
	s_ashr_i32 s87, s86, 31
	s_lshl_b64 s[0:1], s[86:87], 19
	s_add_u32 s88, s19, s0
	s_addc_u32 s89, s20, s1
	s_and_b64 s[0:1], s[12:13], exec
	s_cselect_b32 s36, s89, s17
	s_cselect_b32 s37, s88, s16
	s_ashr_i32 s85, s84, 31
	s_lshl_b64 s[0:1], s[84:85], 19
	s_add_u32 s90, s52, s0
	s_addc_u32 s91, s53, s1
	s_and_b64 s[0:1], s[12:13], exec
	s_cselect_b32 s38, s91, s3
	s_cselect_b32 s39, s90, s2
	s_add_u32 s0, s16, 0x40080
	s_addc_u32 s1, s17, 0
	s_add_u32 s40, s2, 0x100
	s_addc_u32 s41, s3, 0
	s_mov_b32 s42, -2
	ds_read_b128 v[82:85], v183
	ds_read_b128 v[134:137], v183 offset:1024
	ds_read_b128 v[138:141], v183 offset:2048
	ds_read_b128 v[188:191], v183 offset:3072
	ds_read_b128 v[192:195], v184
	ds_read_b128 v[196:199], v184 offset:1024
	ds_read_b128 v[200:203], v184 offset:2048
	ds_read_b128 v[204:207], v184 offset:3072
	s_add_u32 s2, s0, 0xfffc0080
	s_addc_u32 s3, s1, -1
	s_cmp_eq_u32 s42, 12
	s_cselect_b32 s17, s36, s3
	s_cselect_b32 s16, s37, s2
	s_cselect_b32 s3, s38, s41
	s_cselect_b32 s2, s39, s40
	v_lshl_add_u64 v[228:229], s[0:1], 0, v[152:153]
	s_add_i32 m0, s21, 0xc000
	ds_read_b128 v[208:211], v185
	ds_read_b128 v[212:215], v185 offset:1024
	ds_read_b128 v[216:219], v185 offset:2048
	ds_read_b128 v[220:223], v185 offset:3072
	ds_read_b128 v[224:227], v185 offset:4096
	ds_read_b128 v[232:235], v185 offset:5120
	ds_read_b128 v[236:239], v185 offset:6144
	ds_read_b128 v[240:243], v185 offset:7168
	global_load_lds_dwordx4 v[228:229], off
	v_lshl_add_u64 v[228:229], s[0:1], 0, v[154:155]
	s_add_i32 m0, s21, 0xe000
	s_nop 0
	global_load_lds_dwordx4 v[228:229], off
	s_waitcnt vmcnt(8)
	s_waitcnt lgkmcnt(0)
	s_barrier
	s_setprio 1
	s_waitcnt lgkmcnt(0)
	v_mfma_f32_16x16x32_bf16 v[122:125], v[82:85], v[208:211], 0
	v_mfma_f32_16x16x32_bf16 v[130:133], v[138:141], v[208:211], 0
	v_mfma_f32_16x16x32_bf16 v[106:109], v[82:85], v[216:219], 0
	v_mfma_f32_16x16x32_bf16 v[118:121], v[138:141], v[216:219], 0
	v_mfma_f32_16x16x32_bf16 v[90:93], v[82:85], v[224:227], 0
	v_mfma_f32_16x16x32_bf16 v[102:105], v[138:141], v[224:227], 0
	v_mfma_f32_16x16x32_bf16 v[68:71], v[82:85], v[236:239], 0
	v_mfma_f32_16x16x32_bf16 v[76:79], v[138:141], v[236:239], 0
	v_mfma_f32_16x16x32_bf16 v[122:125], v[134:137], v[212:215], v[122:125]
	v_mfma_f32_16x16x32_bf16 v[130:133], v[188:191], v[212:215], v[130:133]
	v_mfma_f32_16x16x32_bf16 v[106:109], v[134:137], v[220:223], v[106:109]
	v_mfma_f32_16x16x32_bf16 v[118:121], v[188:191], v[220:223], v[118:121]
	v_mfma_f32_16x16x32_bf16 v[90:93], v[134:137], v[232:235], v[90:93]
	v_mfma_f32_16x16x32_bf16 v[102:105], v[188:191], v[232:235], v[102:105]
	v_mfma_f32_16x16x32_bf16 v[68:71], v[134:137], v[240:243], v[68:71]
	v_mfma_f32_16x16x32_bf16 v[76:79], v[188:191], v[240:243], v[76:79]
	s_setprio 0
	s_setprio 1
	v_mfma_f32_16x16x32_bf16 v[126:129], v[192:195], v[208:211], 0
	v_mfma_f32_16x16x32_bf16 v[114:117], v[200:203], v[208:211], 0
	v_mfma_f32_16x16x32_bf16 v[110:113], v[192:195], v[216:219], 0
	v_mfma_f32_16x16x32_bf16 v[94:97], v[200:203], v[216:219], 0
	v_mfma_f32_16x16x32_bf16 v[98:101], v[192:195], v[224:227], 0
	v_mfma_f32_16x16x32_bf16 v[86:89], v[200:203], v[224:227], 0
	v_mfma_f32_16x16x32_bf16 v[72:75], v[192:195], v[236:239], 0
	v_mfma_f32_16x16x32_bf16 v[48:51], v[200:203], v[236:239], 0
	v_mfma_f32_16x16x32_bf16 v[126:129], v[196:199], v[212:215], v[126:129]
	v_mfma_f32_16x16x32_bf16 v[114:117], v[204:207], v[212:215], v[114:117]
	v_mfma_f32_16x16x32_bf16 v[110:113], v[196:199], v[220:223], v[110:113]
	v_mfma_f32_16x16x32_bf16 v[94:97], v[204:207], v[220:223], v[94:97]
	v_mfma_f32_16x16x32_bf16 v[98:101], v[196:199], v[232:235], v[98:101]
	v_mfma_f32_16x16x32_bf16 v[86:89], v[204:207], v[232:235], v[86:89]
	v_mfma_f32_16x16x32_bf16 v[72:75], v[196:199], v[240:243], v[72:75]
	v_mfma_f32_16x16x32_bf16 v[48:51], v[204:207], v[240:243], v[48:51]
	s_setprio 0
	s_barrier
	s_add_i32 s33, s30, s18
	v_lshl_add_u64 v[228:229], s[2:3], 0, v[142:143]
	s_mov_b32 m0, s33
	ds_read_b128 v[208:211], v185 offset:16384
	ds_read_b128 v[212:215], v185 offset:17408
	ds_read_b128 v[216:219], v185 offset:18432
	ds_read_b128 v[220:223], v185 offset:19456
	ds_read_b128 v[224:227], v185 offset:20480
	ds_read_b128 v[232:235], v185 offset:21504
	ds_read_b128 v[236:239], v185 offset:22528
	ds_read_b128 v[240:243], v185 offset:23552
	global_load_lds_dwordx4 v[228:229], off
	s_add_i32 m0, s33, 0x2000
	s_add_u32 s44, s2, 0x40000
	v_lshl_add_u64 v[244:245], s[2:3], 0, v[144:145]
	s_addc_u32 s45, s3, 0
	s_add_i32 s33, s31, s18
	global_load_lds_dwordx4 v[244:245], off
	v_lshl_add_u64 v[246:247], s[44:45], 0, v[142:143]
	s_mov_b32 m0, s33
	v_lshl_add_u64 v[248:249], s[16:17], 0, v[144:145]
	global_load_lds_dwordx4 v[246:247], off
	v_lshl_add_u64 v[246:247], s[44:45], 0, v[144:145]
	s_add_i32 m0, s33, 0x2000
	s_nop 0
	global_load_lds_dwordx4 v[246:247], off
	v_lshl_add_u64 v[246:247], s[16:17], 0, v[142:143]
	s_mov_b32 m0, s21
	s_nop 0
	global_load_lds_dwordx4 v[246:247], off
	s_mov_b32 m0, s22
	s_nop 0
	global_load_lds_dwordx4 v[248:249], off
	s_waitcnt vmcnt(8)
	s_waitcnt lgkmcnt(0)
	s_barrier
; #define PG8_STAGE(bufoff, gbase, voff) do { _Pragma("unroll") for (int _i = 0; _i < 2; ++_i) \
;         __builtin_amdgcn_global_load_lds((const unsigned*)((const char*)(gbase) + (voff)[_i]), (PG8_LAS unsigned*)(lds + (bufoff) + ldsw + _i * 8192), 16, 0, 0); } while (0)
; #define PG8_LDA(dst, b, h) do { _Pragma("unroll") for (int m = 0; m < 4; ++m) _Pragma("unroll") for (int k = 0; k < 2; ++k) dst[m][k] = *(const PG8_LAS bf16x8*)(lds + PG8_SA(b, h) + aoff + m * 2048 + k * 1024); } while (0)
; #define PG8_LDB(dst, b, h) do { _Pragma("unroll") for (int n = 0; n < 2; ++n) _Pragma("unroll") for (int k = 0; k < 2; ++k) dst[n][k] = *(const PG8_LAS bf16x8*)(lds + PG8_SB(b, h) + boff + n * 2048 + k * 1024); } while (0)
; #define PG8_MMA(ai, bj, At, Bt) do { __builtin_amdgcn_s_setprio(1); _Pragma("unroll") for (int m = 0; m < 4; ++m) _Pragma("unroll") for (int n = 0; n < 2; ++n) _Pragma("unroll") for (int k = 0; k < 2; ++k) \
;         acc[ai][bj][m][n] = __builtin_amdgcn_mfma_f32_16x16x32_bf16(Bt[n][k], At[m][k], acc[ai][bj][m][n], 0, 0, 0); __builtin_amdgcn_s_setprio(0); } while (0)
; #define PG8_WAIT_V(n) asm volatile("s_waitcnt vmcnt(" #n ")" ::: "memory")
; #define PG8_WAIT_L(n) asm volatile("s_waitcnt lgkmcnt(" #n ")" ::: "memory")
; #define PG8_BAR __builtin_amdgcn_s_barrier()
; #define PG8_SCHED __builtin_amdgcn_sched_barrier(0)
; template <class Epi, class Sched, bool ALIGN_EPI = false, bool SP2 = false>
; __device__ __forceinline__ void gemm_phase(PG8_LAS unsigned char* lds, const Gemm g, const Sched& S, const Epi& E) {
;     ...
;             PG8_LDA(At, 0, 1); PG8_STAGE(PG8_SB(0, 0), b2, voffB); PG8_STAGE(PG8_SB(0, 1), b2 + hstep, voffB); PG8_STAGE(PG8_SA(0, 0), a2, voffA);
;             PG8_WAIT_V(8); PG8_WAIT_L(0); PG8_BAR; PG8_MMA(1, 0, At, B0); PG8_MMA(1, 1, At, B1); PG8_BAR; PG8_SCHED;
;             PG8_LDB(B0, 1, 0); PG8_LDB(B1, 1, 1); PG8_SCHED; PG8_LDA(At, 1, 0); PG8_STAGE(PG8_SA(0, 1), a2 + hstep, voffA);
;             PG8_WAIT_V(8); PG8_WAIT_L(0); PG8_BAR; PG8_MMA(0, 0, At, B0); PG8_MMA(0, 1, At, B1); PG8_BAR; PG8_SCHED;
;             PG8_LDA(At, 1, 1); PG8_STAGE(PG8_SB(1, 0), b3, voffB); PG8_STAGE(PG8_SB(1, 1), b3 + hstep, voffB); PG8_STAGE(PG8_SA(1, 0), a3, voffA);
	s_setprio 1
	s_waitcnt lgkmcnt(0)
	v_mfma_f32_16x16x32_bf16 v[44:47], v[82:85], v[208:211], 0
	v_mfma_f32_16x16x32_bf16 v[60:63], v[138:141], v[208:211], 0
	v_mfma_f32_16x16x32_bf16 v[28:31], v[82:85], v[216:219], 0
	v_mfma_f32_16x16x32_bf16 v[40:43], v[138:141], v[216:219], 0
	v_mfma_f32_16x16x32_bf16 v[12:15], v[82:85], v[224:227], 0
	v_mfma_f32_16x16x32_bf16 v[24:27], v[138:141], v[224:227], 0
	v_mfma_f32_16x16x32_bf16 v[4:7], v[82:85], v[236:239], 0
	v_mfma_f32_16x16x32_bf16 v[64:67], v[138:141], v[236:239], 0
	v_mfma_f32_16x16x32_bf16 v[44:47], v[134:137], v[212:215], v[44:47]
	v_mfma_f32_16x16x32_bf16 v[60:63], v[188:191], v[212:215], v[60:63]
	v_mfma_f32_16x16x32_bf16 v[28:31], v[134:137], v[220:223], v[28:31]
	v_mfma_f32_16x16x32_bf16 v[40:43], v[188:191], v[220:223], v[40:43]
	v_mfma_f32_16x16x32_bf16 v[12:15], v[134:137], v[232:235], v[12:15]
	v_mfma_f32_16x16x32_bf16 v[24:27], v[188:191], v[232:235], v[24:27]
	v_mfma_f32_16x16x32_bf16 v[4:7], v[134:137], v[240:243], v[4:7]
	v_mfma_f32_16x16x32_bf16 v[64:67], v[188:191], v[240:243], v[64:67]
	s_setprio 0
	s_setprio 1
	v_mfma_f32_16x16x32_bf16 v[56:59], v[192:195], v[208:211], 0
	v_mfma_f32_16x16x32_bf16 v[32:35], v[200:203], v[208:211], 0
	v_mfma_f32_16x16x32_bf16 v[36:39], v[192:195], v[216:219], 0
	v_mfma_f32_16x16x32_bf16 v[16:19], v[200:203], v[216:219], 0
	v_mfma_f32_16x16x32_bf16 v[20:23], v[192:195], v[224:227], 0
	v_mfma_f32_16x16x32_bf16 v[8:11], v[200:203], v[224:227], 0
	v_mfma_f32_16x16x32_bf16 v[52:55], v[192:195], v[236:239], 0
	v_mfma_f32_16x16x32_bf16 v[0:3], v[200:203], v[236:239], 0
	v_mfma_f32_16x16x32_bf16 v[56:59], v[196:199], v[212:215], v[56:59]
	v_mfma_f32_16x16x32_bf16 v[32:35], v[204:207], v[212:215], v[32:35]
	v_mfma_f32_16x16x32_bf16 v[36:39], v[196:199], v[220:223], v[36:39]
	v_mfma_f32_16x16x32_bf16 v[16:19], v[204:207], v[220:223], v[16:19]
	v_mfma_f32_16x16x32_bf16 v[20:23], v[196:199], v[232:235], v[20:23]
	v_mfma_f32_16x16x32_bf16 v[8:11], v[204:207], v[232:235], v[8:11]
	v_mfma_f32_16x16x32_bf16 v[52:55], v[196:199], v[240:243], v[52:55]
	v_mfma_f32_16x16x32_bf16 v[0:3], v[204:207], v[240:243], v[0:3]
	s_setprio 0
	s_barrier
	s_add_i32 s33, 0, 0x18000
	v_add_u32_e32 v146, s33, v173
	s_add_i32 s43, 0, 0x1c000
	ds_read_b128 v[82:85], v146
	ds_read_b128 v[134:137], v146 offset:1024
	ds_read_b128 v[138:141], v146 offset:2048
	ds_read_b128 v[188:191], v146 offset:3072
	v_add_u32_e32 v146, s43, v173
	ds_read_b128 v[192:195], v146
	ds_read_b128 v[196:199], v146 offset:1024
	ds_read_b128 v[200:203], v146 offset:2048
	ds_read_b128 v[204:207], v146 offset:3072
	s_add_u32 s16, s16, 0x40000
	s_addc_u32 s17, s17, 0
	s_mov_b32 m0, s23
	v_lshl_add_u64 v[250:251], s[16:17], 0, v[142:143]
	ds_read_b128 v[208:211], v185 offset:32768
	ds_read_b128 v[212:215], v185 offset:33792
	ds_read_b128 v[216:219], v185 offset:34816
	ds_read_b128 v[220:223], v185 offset:35840
	ds_read_b128 v[224:227], v185 offset:36864
	ds_read_b128 v[232:235], v185 offset:37888
	ds_read_b128 v[236:239], v185 offset:38912
	ds_read_b128 v[240:243], v185 offset:39936
	global_load_lds_dwordx4 v[250:251], off
	v_lshl_add_u64 v[250:251], s[16:17], 0, v[144:145]
	s_mov_b32 m0, s24
	s_nop 0
	global_load_lds_dwordx4 v[250:251], off
	s_waitcnt vmcnt(8)
	s_waitcnt lgkmcnt(0)
	s_barrier
	s_setprio 1
	s_waitcnt lgkmcnt(0)
	v_mfma_f32_16x16x32_bf16 v[122:125], v[82:85], v[208:211], v[122:125]
	v_mfma_f32_16x16x32_bf16 v[130:133], v[138:141], v[208:211], v[130:133]
	v_mfma_f32_16x16x32_bf16 v[106:109], v[82:85], v[216:219], v[106:109]
	v_mfma_f32_16x16x32_bf16 v[118:121], v[138:141], v[216:219], v[118:121]
	v_mfma_f32_16x16x32_bf16 v[90:93], v[82:85], v[224:227], v[90:93]
	v_mfma_f32_16x16x32_bf16 v[102:105], v[138:141], v[224:227], v[102:105]
	v_mfma_f32_16x16x32_bf16 v[68:71], v[82:85], v[236:239], v[68:71]
	v_mfma_f32_16x16x32_bf16 v[76:79], v[138:141], v[236:239], v[76:79]
	v_mfma_f32_16x16x32_bf16 v[122:125], v[134:137], v[212:215], v[122:125]
	v_mfma_f32_16x16x32_bf16 v[130:133], v[188:191], v[212:215], v[130:133]
	v_mfma_f32_16x16x32_bf16 v[106:109], v[134:137], v[220:223], v[106:109]
	v_mfma_f32_16x16x32_bf16 v[118:121], v[188:191], v[220:223], v[118:121]
	v_mfma_f32_16x16x32_bf16 v[90:93], v[134:137], v[232:235], v[90:93]
	v_mfma_f32_16x16x32_bf16 v[102:105], v[188:191], v[232:235], v[102:105]
	v_mfma_f32_16x16x32_bf16 v[68:71], v[134:137], v[240:243], v[68:71]
	v_mfma_f32_16x16x32_bf16 v[76:79], v[188:191], v[240:243], v[76:79]
	s_setprio 0
	s_setprio 1
	v_mfma_f32_16x16x32_bf16 v[126:129], v[192:195], v[208:211], v[126:129]
	v_mfma_f32_16x16x32_bf16 v[114:117], v[200:203], v[208:211], v[114:117]
	v_mfma_f32_16x16x32_bf16 v[110:113], v[192:195], v[216:219], v[110:113]
	v_mfma_f32_16x16x32_bf16 v[94:97], v[200:203], v[216:219], v[94:97]
	v_mfma_f32_16x16x32_bf16 v[98:101], v[192:195], v[224:227], v[98:101]
	v_mfma_f32_16x16x32_bf16 v[86:89], v[200:203], v[224:227], v[86:89]
	v_mfma_f32_16x16x32_bf16 v[72:75], v[192:195], v[236:239], v[72:75]
	v_mfma_f32_16x16x32_bf16 v[48:51], v[200:203], v[236:239], v[48:51]
	v_mfma_f32_16x16x32_bf16 v[126:129], v[196:199], v[212:215], v[126:129]
	v_mfma_f32_16x16x32_bf16 v[114:117], v[204:207], v[212:215], v[114:117]
	v_mfma_f32_16x16x32_bf16 v[110:113], v[196:199], v[220:223], v[110:113]
	v_mfma_f32_16x16x32_bf16 v[94:97], v[204:207], v[220:223], v[94:97]
	v_mfma_f32_16x16x32_bf16 v[98:101], v[196:199], v[232:235], v[98:101]
	v_mfma_f32_16x16x32_bf16 v[86:89], v[204:207], v[232:235], v[86:89]
	v_mfma_f32_16x16x32_bf16 v[72:75], v[196:199], v[240:243], v[72:75]
	v_mfma_f32_16x16x32_bf16 v[48:51], v[204:207], v[240:243], v[48:51]
	s_setprio 0
	s_barrier
; #define PG8_STAGE(bufoff, gbase, voff) do { _Pragma("unroll") for (int _i = 0; _i < 2; ++_i) \
;         __builtin_amdgcn_global_load_lds((const unsigned*)((const char*)(gbase) + (voff)[_i]), (PG8_LAS unsigned*)(lds + (bufoff) + ldsw + _i * 8192), 16, 0, 0); } while (0)
; #define PG8_LDA(dst, b, h) do { _Pragma("unroll") for (int m = 0; m < 4; ++m) _Pragma("unroll") for (int k = 0; k < 2; ++k) dst[m][k] = *(const PG8_LAS bf16x8*)(lds + PG8_SA(b, h) + aoff + m * 2048 + k * 1024); } while (0)
; #define PG8_LDB(dst, b, h) do { _Pragma("unroll") for (int n = 0; n < 2; ++n) _Pragma("unroll") for (int k = 0; k < 2; ++k) dst[n][k] = *(const PG8_LAS bf16x8*)(lds + PG8_SB(b, h) + boff + n * 2048 + k * 1024); } while (0)
; #define PG8_WAIT_V(n) asm volatile("s_waitcnt vmcnt(" #n ")" ::: "memory")
; #define PG8_WAIT_L(n) asm volatile("s_waitcnt lgkmcnt(" #n ")" ::: "memory")
; template <class Epi, class Sched, bool ALIGN_EPI = false, bool SP2 = false>
; __device__ __forceinline__ void gemm_phase(PG8_LAS unsigned char* lds, const Gemm g, const Sched& S, const Epi& E) {
;     ...
;         for (int t = 0; t < nt; t += 2) {
;             if constexpr (Epi::MID) { if (t == nt / 2) E.mid(acc, cur, wr, fr, lds); }
;             const bool last = (t == nt - 2);
;             const char* a1 = cA + (size_t)(t + 1) * kstep;
;             const char* a2 = last ? nA : cA + (size_t)(t + 2) * kstep; const char* b2 = last ? nB : cB + (size_t)(t + 2) * kstep;
;             const char* a3 = a2 + kstep; const char* b3 = b2 + kstep;
;             if (last && has_next) S.a_ready(nxt);
;             if constexpr (SP2) {
;             PG8_LDB(B0, 0, 0); PG8_LDB(B1, 0, 1); PG8_SCHED; PG8_LDA(At, 0, 0); PG8_STAGE(PG8_SA(1, 1), a1 + hstep, voffA);
;             PG8_WAIT_V(8); PG8_WAIT_L(0); PG8_BAR; PG8_MMA(0, 0, At, B0); PG8_MMA(0, 1, At, B1); PG8_BAR; PG8_SCHED;
;     ...
;             PG8_LDB(B0, 1, 0); PG8_LDB(B1, 1, 1); PG8_SCHED; PG8_LDA(At, 1, 0); PG8_STAGE(PG8_SA(0, 1), a2 + hstep, voffA);
;             PG8_WAIT_V(8); PG8_WAIT_L(0); PG8_BAR; PG8_MMA(0, 0, At, B0); PG8_MMA(0, 1, At, B1); PG8_BAR; PG8_SCHED;
;             PG8_LDA(At, 1, 1); PG8_STAGE(PG8_SB(1, 0), b3, voffB); PG8_STAGE(PG8_SB(1, 1), b3 + hstep, voffB); PG8_STAGE(PG8_SA(1, 0), a3, voffA);
;             PG8_WAIT_V(8); PG8_WAIT_L(0); PG8_BAR; PG8_MMA(1, 0, At, B0); PG8_MMA(1, 1, At, B1); PG8_BAR; PG8_SCHED;
	s_add_i32 s16, s33, s18
	v_lshl_add_u64 v[228:229], v[228:229], 0, s[66:67]
	s_mov_b32 m0, s16
	ds_read_b128 v[208:211], v185 offset:49152
	ds_read_b128 v[212:215], v185 offset:50176
	ds_read_b128 v[216:219], v185 offset:51200
	ds_read_b128 v[220:223], v185 offset:52224
	ds_read_b128 v[224:227], v185 offset:53248
	ds_read_b128 v[232:235], v185 offset:54272
	ds_read_b128 v[236:239], v185 offset:55296
	ds_read_b128 v[240:243], v185 offset:56320
	global_load_lds_dwordx4 v[228:229], off
	s_add_i32 m0, s16, 0x2000
	s_add_u32 s2, s2, 0x40080
	v_lshl_add_u64 v[228:229], v[244:245], 0, s[66:67]
	s_addc_u32 s3, s3, 0
	s_add_i32 s16, s43, s18
	global_load_lds_dwordx4 v[228:229], off
	v_lshl_add_u64 v[228:229], s[2:3], 0, v[142:143]
	s_mov_b32 m0, s16
	s_nop 0
	global_load_lds_dwordx4 v[228:229], off
	v_lshl_add_u64 v[228:229], s[2:3], 0, v[144:145]
	s_add_i32 m0, s16, 0x2000
	s_nop 0
	global_load_lds_dwordx4 v[228:229], off
	v_lshl_add_u64 v[228:229], v[246:247], 0, s[66:67]
	s_mov_b32 m0, s27
	s_nop 0
	global_load_lds_dwordx4 v[228:229], off
	v_lshl_add_u64 v[228:229], v[248:249], 0, s[66:67]
	s_mov_b32 m0, s28
	s_nop 0
	global_load_lds_dwordx4 v[228:229], off
	s_waitcnt vmcnt(8)
	s_waitcnt lgkmcnt(0)
	s_barrier
	s_setprio 1
	s_waitcnt lgkmcnt(0)
	v_mfma_f32_16x16x32_bf16 v[44:47], v[82:85], v[208:211], v[44:47]
	v_mfma_f32_16x16x32_bf16 v[60:63], v[138:141], v[208:211], v[60:63]
	v_mfma_f32_16x16x32_bf16 v[28:31], v[82:85], v[216:219], v[28:31]
	v_mfma_f32_16x16x32_bf16 v[40:43], v[138:141], v[216:219], v[40:43]
	v_mfma_f32_16x16x32_bf16 v[12:15], v[82:85], v[224:227], v[12:15]
	v_mfma_f32_16x16x32_bf16 v[24:27], v[138:141], v[224:227], v[24:27]
	v_mfma_f32_16x16x32_bf16 v[4:7], v[82:85], v[236:239], v[4:7]
	v_mfma_f32_16x16x32_bf16 v[64:67], v[138:141], v[236:239], v[64:67]
	v_mfma_f32_16x16x32_bf16 v[44:47], v[134:137], v[212:215], v[44:47]
	v_mfma_f32_16x16x32_bf16 v[60:63], v[188:191], v[212:215], v[60:63]
	v_mfma_f32_16x16x32_bf16 v[28:31], v[134:137], v[220:223], v[28:31]
	v_mfma_f32_16x16x32_bf16 v[40:43], v[188:191], v[220:223], v[40:43]
	v_mfma_f32_16x16x32_bf16 v[12:15], v[134:137], v[232:235], v[12:15]
	v_mfma_f32_16x16x32_bf16 v[24:27], v[188:191], v[232:235], v[24:27]
	v_mfma_f32_16x16x32_bf16 v[4:7], v[134:137], v[240:243], v[4:7]
	v_mfma_f32_16x16x32_bf16 v[64:67], v[188:191], v[240:243], v[64:67]
	s_setprio 0
	s_setprio 1
	v_mfma_f32_16x16x32_bf16 v[56:59], v[192:195], v[208:211], v[56:59]
	v_mfma_f32_16x16x32_bf16 v[32:35], v[200:203], v[208:211], v[32:35]
	v_mfma_f32_16x16x32_bf16 v[36:39], v[192:195], v[216:219], v[36:39]
	v_mfma_f32_16x16x32_bf16 v[16:19], v[200:203], v[216:219], v[16:19]
	v_mfma_f32_16x16x32_bf16 v[20:23], v[192:195], v[224:227], v[20:23]
	v_mfma_f32_16x16x32_bf16 v[8:11], v[200:203], v[224:227], v[8:11]
	v_mfma_f32_16x16x32_bf16 v[52:55], v[192:195], v[236:239], v[52:55]
	v_mfma_f32_16x16x32_bf16 v[0:3], v[200:203], v[236:239], v[0:3]
	s_add_i32 s42, s42, 2
	s_add_u32 s0, s0, 0x100
	s_addc_u32 s1, s1, 0
	s_add_u32 s40, s40, 0x100
	s_addc_u32 s41, s41, 0
	v_mfma_f32_16x16x32_bf16 v[56:59], v[196:199], v[212:215], v[56:59]
	v_mfma_f32_16x16x32_bf16 v[32:35], v[204:207], v[212:215], v[32:35]
	v_mfma_f32_16x16x32_bf16 v[36:39], v[196:199], v[220:223], v[36:39]
	v_mfma_f32_16x16x32_bf16 v[16:19], v[204:207], v[220:223], v[16:19]
	v_mfma_f32_16x16x32_bf16 v[20:23], v[196:199], v[232:235], v[20:23]
	v_mfma_f32_16x16x32_bf16 v[8:11], v[204:207], v[232:235], v[8:11]
	v_mfma_f32_16x16x32_bf16 v[52:55], v[196:199], v[240:243], v[52:55]
	v_mfma_f32_16x16x32_bf16 v[0:3], v[204:207], v[240:243], v[0:3]
	s_setprio 0
	s_barrier
.LBB0_133:
	ds_read_b128 v[82:85], v183
	ds_read_b128 v[134:137], v183 offset:1024
	ds_read_b128 v[138:141], v183 offset:2048
	ds_read_b128 v[188:191], v183 offset:3072
	ds_read_b128 v[192:195], v184
	ds_read_b128 v[196:199], v184 offset:1024
	ds_read_b128 v[200:203], v184 offset:2048
	ds_read_b128 v[204:207], v184 offset:3072
	s_add_u32 s2, s0, 0xfffc0080
	s_addc_u32 s3, s1, -1
	s_cmp_eq_u32 s42, 12
	s_cselect_b32 s17, s36, s3
	s_cselect_b32 s16, s37, s2
	s_cselect_b32 s3, s38, s41
	s_cselect_b32 s2, s39, s40
	v_lshl_add_u64 v[228:229], s[0:1], 0, v[152:153]
	s_add_i32 m0, s21, 0xc000
	ds_read_b128 v[208:211], v185
	ds_read_b128 v[212:215], v185 offset:1024
	ds_read_b128 v[216:219], v185 offset:2048
	ds_read_b128 v[220:223], v185 offset:3072
	ds_read_b128 v[224:227], v185 offset:4096
	ds_read_b128 v[232:235], v185 offset:5120
	ds_read_b128 v[236:239], v185 offset:6144
	ds_read_b128 v[240:243], v185 offset:7168
	global_load_lds_dwordx4 v[228:229], off
	v_lshl_add_u64 v[228:229], s[0:1], 0, v[154:155]
	s_add_i32 m0, s21, 0xe000
	s_nop 0
	global_load_lds_dwordx4 v[228:229], off
	s_waitcnt vmcnt(8)
	s_waitcnt lgkmcnt(0)
	s_barrier
; #define PG8_WAIT_V(n) asm volatile("s_waitcnt vmcnt(" #n ")" ::: "memory")
; #define PG8_WAIT_L(n) asm volatile("s_waitcnt lgkmcnt(" #n ")" ::: "memory")
; template <class Epi, class Sched, bool ALIGN_EPI = false, bool SP2 = false>
; __device__ __forceinline__ void gemm_phase(PG8_LAS unsigned char* lds, const Gemm g, const Sched& S, const Epi& E) {
;     ...
;             PG8_LDB(B0, 0, 0); PG8_LDB(B1, 0, 1); PG8_SCHED; PG8_LDA(At, 0, 0); PG8_STAGE(PG8_SA(1, 1), a1 + hstep, voffA);
;             PG8_WAIT_V(8); PG8_WAIT_L(0); PG8_BAR; PG8_MMA(0, 0, At, B0); PG8_MMA(0, 1, At, B1); PG8_BAR; PG8_SCHED;
;             if constexpr (Epi::XPF) {
;             const bool xsel = last && !has_next;
;             const char* xt = (const char*)E.x + ((size_t)cur.pm * BM * 1024 + (size_t)cur.pn * BM) * 4;
;             const unsigned vB[2] = {xsel ? voffX[0] : voffB[0], xsel ? voffX[1] : voffB[1]}, vA[2] = {xsel ? voffX[0] : voffA[0], xsel ? voffX[1] : voffA[1]};
;     ...
;             PG8_LDA(At, 0, 1); PG8_STAGE(PG8_SB(0, 0), xsel ? PG8_XR(0) : b2, vB); PG8_STAGE(PG8_SB(0, 1), xsel ? PG8_XR(1) : b2 + hstep, vB); PG8_STAGE(PG8_SA(0, 0), xsel ? PG8_XR(2) : a2, vA);
;             PG8_WAIT_V(8); PG8_WAIT_L(0); PG8_BAR; PG8_MMA(1, 0, At, B0); PG8_MMA(1, 1, At, B1); PG8_BAR; PG8_SCHED;
;             PG8_LDB(B0, 1, 0); PG8_LDB(B1, 1, 1); PG8_SCHED; PG8_LDA(At, 1, 0); PG8_STAGE(PG8_SA(0, 1), xsel ? PG8_XR(3) : a2 + hstep, vA);
;             PG8_WAIT_V(8); PG8_WAIT_L(0); PG8_BAR; PG8_MMA(0, 0, At, B0); PG8_MMA(0, 1, At, B1); PG8_BAR; PG8_SCHED;
;             PG8_LDA(At, 1, 1); PG8_STAGE(PG8_SB(1, 0), xsel ? PG8_XR(4) : b3, vB); PG8_STAGE(PG8_SB(1, 1), xsel ? PG8_XR(5) : b3 + hstep, vB); PG8_STAGE(PG8_SA(1, 0), xsel ? PG8_XR(6) : a3, vA);
;             PG8_WAIT_V(8); PG8_WAIT_L(0); PG8_BAR; PG8_MMA(1, 0, At, B0); PG8_MMA(1, 1, At, B1); PG8_BAR; PG8_SCHED;
;     ...
;             } else {
;             PG8_LDA(At, 0, 1); PG8_STAGE(PG8_SB(0, 0), b2, voffB); PG8_STAGE(PG8_SB(0, 1), b2 + hstep, voffB); PG8_STAGE(PG8_SA(0, 0), a2, voffA);
;             PG8_WAIT_V(8); PG8_WAIT_L(0); PG8_BAR; PG8_MMA(1, 0, At, B0); PG8_MMA(1, 1, At, B1); PG8_BAR; PG8_SCHED;
;             PG8_LDB(B0, 1, 0); PG8_LDB(B1, 1, 1); PG8_SCHED; PG8_LDA(At, 1, 0); PG8_STAGE(PG8_SA(0, 1), a2 + hstep, voffA);
;             PG8_WAIT_V(8); PG8_WAIT_L(0); PG8_BAR; PG8_MMA(0, 0, At, B0); PG8_MMA(0, 1, At, B1); PG8_BAR; PG8_SCHED;
	s_setprio 1
	s_waitcnt lgkmcnt(0)
	v_mfma_f32_16x16x32_bf16 v[122:125], v[82:85], v[208:211], v[122:125]
	v_mfma_f32_16x16x32_bf16 v[130:133], v[138:141], v[208:211], v[130:133]
	v_mfma_f32_16x16x32_bf16 v[106:109], v[82:85], v[216:219], v[106:109]
	v_mfma_f32_16x16x32_bf16 v[118:121], v[138:141], v[216:219], v[118:121]
	v_mfma_f32_16x16x32_bf16 v[90:93], v[82:85], v[224:227], v[90:93]
	v_mfma_f32_16x16x32_bf16 v[102:105], v[138:141], v[224:227], v[102:105]
	v_mfma_f32_16x16x32_bf16 v[68:71], v[82:85], v[236:239], v[68:71]
	v_mfma_f32_16x16x32_bf16 v[76:79], v[138:141], v[236:239], v[76:79]
	v_mfma_f32_16x16x32_bf16 v[122:125], v[134:137], v[212:215], v[122:125]
	v_mfma_f32_16x16x32_bf16 v[130:133], v[188:191], v[212:215], v[130:133]
	v_mfma_f32_16x16x32_bf16 v[106:109], v[134:137], v[220:223], v[106:109]
	v_mfma_f32_16x16x32_bf16 v[118:121], v[188:191], v[220:223], v[118:121]
	v_mfma_f32_16x16x32_bf16 v[90:93], v[134:137], v[232:235], v[90:93]
	v_mfma_f32_16x16x32_bf16 v[102:105], v[188:191], v[232:235], v[102:105]
	v_mfma_f32_16x16x32_bf16 v[68:71], v[134:137], v[240:243], v[68:71]
	v_mfma_f32_16x16x32_bf16 v[76:79], v[188:191], v[240:243], v[76:79]
	s_setprio 0
	s_setprio 1
	v_mfma_f32_16x16x32_bf16 v[126:129], v[192:195], v[208:211], v[126:129]
	v_mfma_f32_16x16x32_bf16 v[114:117], v[200:203], v[208:211], v[114:117]
	v_mfma_f32_16x16x32_bf16 v[110:113], v[192:195], v[216:219], v[110:113]
	v_mfma_f32_16x16x32_bf16 v[94:97], v[200:203], v[216:219], v[94:97]
	v_mfma_f32_16x16x32_bf16 v[98:101], v[192:195], v[224:227], v[98:101]
	v_mfma_f32_16x16x32_bf16 v[86:89], v[200:203], v[224:227], v[86:89]
	v_mfma_f32_16x16x32_bf16 v[72:75], v[192:195], v[236:239], v[72:75]
	v_mfma_f32_16x16x32_bf16 v[48:51], v[200:203], v[236:239], v[48:51]
	v_mfma_f32_16x16x32_bf16 v[126:129], v[196:199], v[212:215], v[126:129]
	v_mfma_f32_16x16x32_bf16 v[114:117], v[204:207], v[212:215], v[114:117]
	v_mfma_f32_16x16x32_bf16 v[110:113], v[196:199], v[220:223], v[110:113]
	v_mfma_f32_16x16x32_bf16 v[94:97], v[204:207], v[220:223], v[94:97]
	v_mfma_f32_16x16x32_bf16 v[98:101], v[196:199], v[232:235], v[98:101]
	v_mfma_f32_16x16x32_bf16 v[86:89], v[204:207], v[232:235], v[86:89]
	v_mfma_f32_16x16x32_bf16 v[72:75], v[196:199], v[240:243], v[72:75]
	v_mfma_f32_16x16x32_bf16 v[48:51], v[204:207], v[240:243], v[48:51]
	s_setprio 0
	s_barrier
	s_add_i32 s33, s30, s18
	v_lshl_add_u64 v[228:229], s[2:3], 0, v[142:143]
	s_mov_b32 m0, s33
	ds_read_b128 v[208:211], v185 offset:16384
	ds_read_b128 v[212:215], v185 offset:17408
	ds_read_b128 v[216:219], v185 offset:18432
	ds_read_b128 v[220:223], v185 offset:19456
	ds_read_b128 v[224:227], v185 offset:20480
	ds_read_b128 v[232:235], v185 offset:21504
	ds_read_b128 v[236:239], v185 offset:22528
	ds_read_b128 v[240:243], v185 offset:23552
	global_load_lds_dwordx4 v[228:229], off
	s_add_i32 m0, s33, 0x2000
	s_add_u32 s44, s2, 0x40000
	v_lshl_add_u64 v[244:245], s[2:3], 0, v[144:145]
	s_addc_u32 s45, s3, 0
	s_add_i32 s33, s31, s18
	global_load_lds_dwordx4 v[244:245], off
	v_lshl_add_u64 v[246:247], s[44:45], 0, v[142:143]
	s_mov_b32 m0, s33
	v_lshl_add_u64 v[248:249], s[16:17], 0, v[144:145]
	global_load_lds_dwordx4 v[246:247], off
	v_lshl_add_u64 v[246:247], s[44:45], 0, v[144:145]
	s_add_i32 m0, s33, 0x2000
	s_nop 0
	global_load_lds_dwordx4 v[246:247], off
	v_lshl_add_u64 v[246:247], s[16:17], 0, v[142:143]
	s_mov_b32 m0, s21
	s_nop 0
	global_load_lds_dwordx4 v[246:247], off
	s_mov_b32 m0, s22
	s_nop 0
	global_load_lds_dwordx4 v[248:249], off
	s_waitcnt vmcnt(8)
	s_waitcnt lgkmcnt(0)
	s_barrier
	s_setprio 1
	s_waitcnt lgkmcnt(0)
	v_mfma_f32_16x16x32_bf16 v[44:47], v[82:85], v[208:211], v[44:47]
	v_mfma_f32_16x16x32_bf16 v[60:63], v[138:141], v[208:211], v[60:63]
	v_mfma_f32_16x16x32_bf16 v[28:31], v[82:85], v[216:219], v[28:31]
	v_mfma_f32_16x16x32_bf16 v[40:43], v[138:141], v[216:219], v[40:43]
	v_mfma_f32_16x16x32_bf16 v[12:15], v[82:85], v[224:227], v[12:15]
	v_mfma_f32_16x16x32_bf16 v[24:27], v[138:141], v[224:227], v[24:27]
	v_mfma_f32_16x16x32_bf16 v[4:7], v[82:85], v[236:239], v[4:7]
	v_mfma_f32_16x16x32_bf16 v[64:67], v[138:141], v[236:239], v[64:67]
	v_mfma_f32_16x16x32_bf16 v[44:47], v[134:137], v[212:215], v[44:47]
	v_mfma_f32_16x16x32_bf16 v[60:63], v[188:191], v[212:215], v[60:63]
	v_mfma_f32_16x16x32_bf16 v[28:31], v[134:137], v[220:223], v[28:31]
	v_mfma_f32_16x16x32_bf16 v[40:43], v[188:191], v[220:223], v[40:43]
	v_mfma_f32_16x16x32_bf16 v[12:15], v[134:137], v[232:235], v[12:15]
	v_mfma_f32_16x16x32_bf16 v[24:27], v[188:191], v[232:235], v[24:27]
	v_mfma_f32_16x16x32_bf16 v[4:7], v[134:137], v[240:243], v[4:7]
	v_mfma_f32_16x16x32_bf16 v[64:67], v[188:191], v[240:243], v[64:67]
	s_setprio 0
	s_setprio 1
	v_mfma_f32_16x16x32_bf16 v[56:59], v[192:195], v[208:211], v[56:59]
	v_mfma_f32_16x16x32_bf16 v[32:35], v[200:203], v[208:211], v[32:35]
	v_mfma_f32_16x16x32_bf16 v[36:39], v[192:195], v[216:219], v[36:39]
	v_mfma_f32_16x16x32_bf16 v[16:19], v[200:203], v[216:219], v[16:19]
	v_mfma_f32_16x16x32_bf16 v[20:23], v[192:195], v[224:227], v[20:23]
	v_mfma_f32_16x16x32_bf16 v[8:11], v[200:203], v[224:227], v[8:11]
	v_mfma_f32_16x16x32_bf16 v[52:55], v[192:195], v[236:239], v[52:55]
	v_mfma_f32_16x16x32_bf16 v[0:3], v[200:203], v[236:239], v[0:3]
	v_mfma_f32_16x16x32_bf16 v[56:59], v[196:199], v[212:215], v[56:59]
	v_mfma_f32_16x16x32_bf16 v[32:35], v[204:207], v[212:215], v[32:35]
	v_mfma_f32_16x16x32_bf16 v[36:39], v[196:199], v[220:223], v[36:39]
	v_mfma_f32_16x16x32_bf16 v[16:19], v[204:207], v[220:223], v[16:19]
	v_mfma_f32_16x16x32_bf16 v[20:23], v[196:199], v[232:235], v[20:23]
	v_mfma_f32_16x16x32_bf16 v[8:11], v[204:207], v[232:235], v[8:11]
	v_mfma_f32_16x16x32_bf16 v[52:55], v[196:199], v[240:243], v[52:55]
	v_mfma_f32_16x16x32_bf16 v[0:3], v[204:207], v[240:243], v[0:3]
	s_setprio 0
	s_barrier
; #define PG8_STAGE(bufoff, gbase, voff) do { _Pragma("unroll") for (int _i = 0; _i < 2; ++_i) \
;         __builtin_amdgcn_global_load_lds((const unsigned*)((const char*)(gbase) + (voff)[_i]), (PG8_LAS unsigned*)(lds + (bufoff) + ldsw + _i * 8192), 16, 0, 0); } while (0)
; #define PG8_LDA(dst, b, h) do { _Pragma("unroll") for (int m = 0; m < 4; ++m) _Pragma("unroll") for (int k = 0; k < 2; ++k) dst[m][k] = *(const PG8_LAS bf16x8*)(lds + PG8_SA(b, h) + aoff + m * 2048 + k * 1024); } while (0)
; #define PG8_LDB(dst, b, h) do { _Pragma("unroll") for (int n = 0; n < 2; ++n) _Pragma("unroll") for (int k = 0; k < 2; ++k) dst[n][k] = *(const PG8_LAS bf16x8*)(lds + PG8_SB(b, h) + boff + n * 2048 + k * 1024); } while (0)
; #define PG8_MMA(ai, bj, At, Bt) do { __builtin_amdgcn_s_setprio(1); _Pragma("unroll") for (int m = 0; m < 4; ++m) _Pragma("unroll") for (int n = 0; n < 2; ++n) _Pragma("unroll") for (int k = 0; k < 2; ++k) \
;         acc[ai][bj][m][n] = __builtin_amdgcn_mfma_f32_16x16x32_bf16(Bt[n][k], At[m][k], acc[ai][bj][m][n], 0, 0, 0); __builtin_amdgcn_s_setprio(0); } while (0)
; #define PG8_WAIT_V(n) asm volatile("s_waitcnt vmcnt(" #n ")" ::: "memory")
; #define PG8_WAIT_L(n) asm volatile("s_waitcnt lgkmcnt(" #n ")" ::: "memory")
; #define PG8_BAR __builtin_amdgcn_s_barrier()
; #define PG8_SCHED __builtin_amdgcn_sched_barrier(0)
; template <class Epi, class Sched, bool ALIGN_EPI = false, bool SP2 = false>
; __device__ __forceinline__ void gemm_phase(PG8_LAS unsigned char* lds, const Gemm g, const Sched& S, const Epi& E) {
;     ...
;             PG8_LDB(B0, 1, 0); PG8_LDB(B1, 1, 1); PG8_SCHED; PG8_LDA(At, 1, 0); PG8_STAGE(PG8_SA(0, 1), a2 + hstep, voffA);
;             PG8_WAIT_V(8); PG8_WAIT_L(0); PG8_BAR; PG8_MMA(0, 0, At, B0); PG8_MMA(0, 1, At, B1); PG8_BAR; PG8_SCHED;
;             PG8_LDA(At, 1, 1); PG8_STAGE(PG8_SB(1, 0), b3, voffB); PG8_STAGE(PG8_SB(1, 1), b3 + hstep, voffB); PG8_STAGE(PG8_SA(1, 0), a3, voffA);
	s_add_i32 s33, 0, 0x18000
	v_add_u32_e32 v146, s33, v173
	s_add_i32 s43, 0, 0x1c000
	ds_read_b128 v[82:85], v146
	ds_read_b128 v[134:137], v146 offset:1024
	ds_read_b128 v[138:141], v146 offset:2048
	ds_read_b128 v[188:191], v146 offset:3072
	v_add_u32_e32 v146, s43, v173
	ds_read_b128 v[192:195], v146
	ds_read_b128 v[196:199], v146 offset:1024
	ds_read_b128 v[200:203], v146 offset:2048
	ds_read_b128 v[204:207], v146 offset:3072
	s_add_u32 s16, s16, 0x40000
	s_addc_u32 s17, s17, 0
	s_mov_b32 m0, s23
	v_lshl_add_u64 v[250:251], s[16:17], 0, v[142:143]
	ds_read_b128 v[208:211], v185 offset:32768
	ds_read_b128 v[212:215], v185 offset:33792
	ds_read_b128 v[216:219], v185 offset:34816
	ds_read_b128 v[220:223], v185 offset:35840
	ds_read_b128 v[224:227], v185 offset:36864
	ds_read_b128 v[232:235], v185 offset:37888
	ds_read_b128 v[236:239], v185 offset:38912
	ds_read_b128 v[240:243], v185 offset:39936
	global_load_lds_dwordx4 v[250:251], off
	v_lshl_add_u64 v[250:251], s[16:17], 0, v[144:145]
	s_mov_b32 m0, s24
	s_nop 0
	global_load_lds_dwordx4 v[250:251], off
	s_waitcnt vmcnt(8)
	s_waitcnt lgkmcnt(0)
	s_barrier
	s_setprio 1
	s_waitcnt lgkmcnt(0)
	v_mfma_f32_16x16x32_bf16 v[122:125], v[82:85], v[208:211], v[122:125]
	v_mfma_f32_16x16x32_bf16 v[130:133], v[138:141], v[208:211], v[130:133]
	v_mfma_f32_16x16x32_bf16 v[106:109], v[82:85], v[216:219], v[106:109]
	v_mfma_f32_16x16x32_bf16 v[118:121], v[138:141], v[216:219], v[118:121]
	v_mfma_f32_16x16x32_bf16 v[90:93], v[82:85], v[224:227], v[90:93]
	v_mfma_f32_16x16x32_bf16 v[102:105], v[138:141], v[224:227], v[102:105]
	v_mfma_f32_16x16x32_bf16 v[68:71], v[82:85], v[236:239], v[68:71]
	v_mfma_f32_16x16x32_bf16 v[76:79], v[138:141], v[236:239], v[76:79]
	v_mfma_f32_16x16x32_bf16 v[122:125], v[134:137], v[212:215], v[122:125]
	v_mfma_f32_16x16x32_bf16 v[130:133], v[188:191], v[212:215], v[130:133]
	v_mfma_f32_16x16x32_bf16 v[106:109], v[134:137], v[220:223], v[106:109]
	v_mfma_f32_16x16x32_bf16 v[118:121], v[188:191], v[220:223], v[118:121]
	v_mfma_f32_16x16x32_bf16 v[90:93], v[134:137], v[232:235], v[90:93]
	v_mfma_f32_16x16x32_bf16 v[102:105], v[188:191], v[232:235], v[102:105]
	v_mfma_f32_16x16x32_bf16 v[68:71], v[134:137], v[240:243], v[68:71]
	v_mfma_f32_16x16x32_bf16 v[76:79], v[188:191], v[240:243], v[76:79]
	s_setprio 0
	s_setprio 1
	v_mfma_f32_16x16x32_bf16 v[126:129], v[192:195], v[208:211], v[126:129]
	v_mfma_f32_16x16x32_bf16 v[114:117], v[200:203], v[208:211], v[114:117]
	v_mfma_f32_16x16x32_bf16 v[110:113], v[192:195], v[216:219], v[110:113]
	v_mfma_f32_16x16x32_bf16 v[94:97], v[200:203], v[216:219], v[94:97]
	v_mfma_f32_16x16x32_bf16 v[98:101], v[192:195], v[224:227], v[98:101]
	v_mfma_f32_16x16x32_bf16 v[86:89], v[200:203], v[224:227], v[86:89]
	v_mfma_f32_16x16x32_bf16 v[72:75], v[192:195], v[236:239], v[72:75]
	v_mfma_f32_16x16x32_bf16 v[48:51], v[200:203], v[236:239], v[48:51]
	v_mfma_f32_16x16x32_bf16 v[126:129], v[196:199], v[212:215], v[126:129]
	v_mfma_f32_16x16x32_bf16 v[114:117], v[204:207], v[212:215], v[114:117]
	v_mfma_f32_16x16x32_bf16 v[110:113], v[196:199], v[220:223], v[110:113]
	v_mfma_f32_16x16x32_bf16 v[94:97], v[204:207], v[220:223], v[94:97]
	v_mfma_f32_16x16x32_bf16 v[98:101], v[196:199], v[232:235], v[98:101]
	v_mfma_f32_16x16x32_bf16 v[86:89], v[204:207], v[232:235], v[86:89]
	v_mfma_f32_16x16x32_bf16 v[72:75], v[196:199], v[240:243], v[72:75]
	v_mfma_f32_16x16x32_bf16 v[48:51], v[204:207], v[240:243], v[48:51]
	s_setprio 0
	s_barrier
; #define PG8_STAGE(bufoff, gbase, voff) do { _Pragma("unroll") for (int _i = 0; _i < 2; ++_i) \
;         __builtin_amdgcn_global_load_lds((const unsigned*)((const char*)(gbase) + (voff)[_i]), (PG8_LAS unsigned*)(lds + (bufoff) + ldsw + _i * 8192), 16, 0, 0); } while (0)
; #define PG8_LDA(dst, b, h) do { _Pragma("unroll") for (int m = 0; m < 4; ++m) _Pragma("unroll") for (int k = 0; k < 2; ++k) dst[m][k] = *(const PG8_LAS bf16x8*)(lds + PG8_SA(b, h) + aoff + m * 2048 + k * 1024); } while (0)
; #define PG8_LDB(dst, b, h) do { _Pragma("unroll") for (int n = 0; n < 2; ++n) _Pragma("unroll") for (int k = 0; k < 2; ++k) dst[n][k] = *(const PG8_LAS bf16x8*)(lds + PG8_SB(b, h) + boff + n * 2048 + k * 1024); } while (0)
; #define PG8_MMA(ai, bj, At, Bt) do { __builtin_amdgcn_s_setprio(1); _Pragma("unroll") for (int m = 0; m < 4; ++m) _Pragma("unroll") for (int n = 0; n < 2; ++n) _Pragma("unroll") for (int k = 0; k < 2; ++k) \
;         acc[ai][bj][m][n] = __builtin_amdgcn_mfma_f32_16x16x32_bf16(Bt[n][k], At[m][k], acc[ai][bj][m][n], 0, 0, 0); __builtin_amdgcn_s_setprio(0); } while (0)
; #define PG8_WAIT_V(n) asm volatile("s_waitcnt vmcnt(" #n ")" ::: "memory")
; #define PG8_WAIT_L(n) asm volatile("s_waitcnt lgkmcnt(" #n ")" ::: "memory")
; #define PG8_BAR __builtin_amdgcn_s_barrier()
; #define PG8_SCHED __builtin_amdgcn_sched_barrier(0)
; template <class Epi, class Sched, bool ALIGN_EPI = false, bool SP2 = false>
; __device__ __forceinline__ void gemm_phase(PG8_LAS unsigned char* lds, const Gemm g, const Sched& S, const Epi& E) {
;     ...
;             PG8_LDB(B0, 1, 0); PG8_LDB(B1, 1, 1); PG8_SCHED; PG8_LDA(At, 1, 0); PG8_STAGE(PG8_SA(0, 1), a2 + hstep, voffA);
;             PG8_WAIT_V(8); PG8_WAIT_L(0); PG8_BAR; PG8_MMA(0, 0, At, B0); PG8_MMA(0, 1, At, B1); PG8_BAR; PG8_SCHED;
;             PG8_LDA(At, 1, 1); PG8_STAGE(PG8_SB(1, 0), b3, voffB); PG8_STAGE(PG8_SB(1, 1), b3 + hstep, voffB); PG8_STAGE(PG8_SA(1, 0), a3, voffA);
;             PG8_WAIT_V(8); PG8_WAIT_L(0); PG8_BAR; PG8_MMA(1, 0, At, B0); PG8_MMA(1, 1, At, B1); PG8_BAR; PG8_SCHED;
;             }
;             } else {
;     ...
;         }
;         if constexpr (ALIGN_EPI) { if (wr == 0) PG8_BAR; }
;         if constexpr (!Epi::AFTER_DRAIN) { E(acc, cur, wr, wc, fr, fq, lds); S.done(cur); }
;         if (!has_next) break;
	s_add_i32 s16, s33, s18
	v_lshl_add_u64 v[228:229], v[228:229], 0, s[66:67]
	s_mov_b32 m0, s16
	ds_read_b128 v[208:211], v185 offset:49152
	ds_read_b128 v[212:215], v185 offset:50176
	ds_read_b128 v[216:219], v185 offset:51200
	ds_read_b128 v[220:223], v185 offset:52224
	ds_read_b128 v[224:227], v185 offset:53248
	ds_read_b128 v[232:235], v185 offset:54272
	ds_read_b128 v[236:239], v185 offset:55296
	ds_read_b128 v[240:243], v185 offset:56320
	global_load_lds_dwordx4 v[228:229], off
	s_add_i32 m0, s16, 0x2000
	s_add_u32 s2, s2, 0x40080
	v_lshl_add_u64 v[228:229], v[244:245], 0, s[66:67]
	s_addc_u32 s3, s3, 0
	s_add_i32 s16, s43, s18
	global_load_lds_dwordx4 v[228:229], off
	v_lshl_add_u64 v[228:229], s[2:3], 0, v[142:143]
	s_mov_b32 m0, s16
	s_nop 0
	global_load_lds_dwordx4 v[228:229], off
	v_lshl_add_u64 v[228:229], s[2:3], 0, v[144:145]
	s_add_i32 m0, s16, 0x2000
	s_nop 0
	global_load_lds_dwordx4 v[228:229], off
	v_lshl_add_u64 v[228:229], v[246:247], 0, s[66:67]
	s_mov_b32 m0, s27
	s_nop 0
	global_load_lds_dwordx4 v[228:229], off
	v_lshl_add_u64 v[228:229], v[248:249], 0, s[66:67]
	s_mov_b32 m0, s28
	s_nop 0
	global_load_lds_dwordx4 v[228:229], off
	s_waitcnt vmcnt(8)
	s_waitcnt lgkmcnt(0)
	s_barrier
	s_setprio 1
	s_waitcnt lgkmcnt(0)
	v_mfma_f32_16x16x32_bf16 v[44:47], v[82:85], v[208:211], v[44:47]
	v_mfma_f32_16x16x32_bf16 v[60:63], v[138:141], v[208:211], v[60:63]
	v_mfma_f32_16x16x32_bf16 v[28:31], v[82:85], v[216:219], v[28:31]
	v_mfma_f32_16x16x32_bf16 v[40:43], v[138:141], v[216:219], v[40:43]
	v_mfma_f32_16x16x32_bf16 v[12:15], v[82:85], v[224:227], v[12:15]
	v_mfma_f32_16x16x32_bf16 v[24:27], v[138:141], v[224:227], v[24:27]
	v_mfma_f32_16x16x32_bf16 v[4:7], v[82:85], v[236:239], v[4:7]
	v_mfma_f32_16x16x32_bf16 v[64:67], v[138:141], v[236:239], v[64:67]
	v_mfma_f32_16x16x32_bf16 v[44:47], v[134:137], v[212:215], v[44:47]
	v_mfma_f32_16x16x32_bf16 v[60:63], v[188:191], v[212:215], v[60:63]
	v_mfma_f32_16x16x32_bf16 v[28:31], v[134:137], v[220:223], v[28:31]
	v_mfma_f32_16x16x32_bf16 v[40:43], v[188:191], v[220:223], v[40:43]
	v_mfma_f32_16x16x32_bf16 v[12:15], v[134:137], v[232:235], v[12:15]
	v_mfma_f32_16x16x32_bf16 v[24:27], v[188:191], v[232:235], v[24:27]
	v_mfma_f32_16x16x32_bf16 v[4:7], v[134:137], v[240:243], v[4:7]
	v_mfma_f32_16x16x32_bf16 v[64:67], v[188:191], v[240:243], v[64:67]
	s_setprio 0
	s_setprio 1
	v_mfma_f32_16x16x32_bf16 v[56:59], v[192:195], v[208:211], v[56:59]
	v_mfma_f32_16x16x32_bf16 v[32:35], v[200:203], v[208:211], v[32:35]
	v_mfma_f32_16x16x32_bf16 v[36:39], v[192:195], v[216:219], v[36:39]
	v_mfma_f32_16x16x32_bf16 v[16:19], v[200:203], v[216:219], v[16:19]
	v_mfma_f32_16x16x32_bf16 v[20:23], v[192:195], v[224:227], v[20:23]
	v_mfma_f32_16x16x32_bf16 v[8:11], v[200:203], v[224:227], v[8:11]
	v_mfma_f32_16x16x32_bf16 v[52:55], v[192:195], v[236:239], v[52:55]
	v_mfma_f32_16x16x32_bf16 v[0:3], v[200:203], v[236:239], v[0:3]
	s_add_i32 s42, s42, 2
	s_add_u32 s0, s0, 0x100
	s_addc_u32 s1, s1, 0
	s_add_u32 s40, s40, 0x100
	s_addc_u32 s41, s41, 0
	s_cmp_gt_u32 s42, 13
	v_mfma_f32_16x16x32_bf16 v[56:59], v[196:199], v[212:215], v[56:59]
	v_mfma_f32_16x16x32_bf16 v[32:35], v[204:207], v[212:215], v[32:35]
	v_mfma_f32_16x16x32_bf16 v[36:39], v[196:199], v[220:223], v[36:39]
	v_mfma_f32_16x16x32_bf16 v[16:19], v[204:207], v[220:223], v[16:19]
	v_mfma_f32_16x16x32_bf16 v[20:23], v[196:199], v[232:235], v[20:23]
	v_mfma_f32_16x16x32_bf16 v[8:11], v[204:207], v[232:235], v[8:11]
	v_mfma_f32_16x16x32_bf16 v[52:55], v[196:199], v[240:243], v[52:55]
	v_mfma_f32_16x16x32_bf16 v[0:3], v[204:207], v[240:243], v[0:3]
	s_setprio 0
	s_barrier
	s_cbranch_scc0 .LBB0_133
	s_and_b64 vcc, exec, s[70:71]
	s_cbranch_vccnz .LBB0_137
	s_cmp_lt_i32 s60, 9
	s_mov_b64 s[0:1], -1
	s_cbranch_scc1 .LBB0_138

; #define PG8_STAGE(bufoff, gbase, voff) do { _Pragma("unroll") for (int _i = 0; _i < 2; ++_i) \
;         __builtin_amdgcn_global_load_lds((const unsigned*)((const char*)(gbase) + (voff)[_i]), (PG8_LAS unsigned*)(lds + (bufoff) + ldsw + _i * 8192), 16, 0, 0); } while (0)
; #define PG8_LDA(dst, b, h) do { _Pragma("unroll") for (int m = 0; m < 4; ++m) _Pragma("unroll") for (int k = 0; k < 2; ++k) dst[m][k] = *(const PG8_LAS bf16x8*)(lds + PG8_SA(b, h) + aoff + m * 2048 + k * 1024); } while (0)
; #define PG8_LDB(dst, b, h) do { _Pragma("unroll") for (int n = 0; n < 2; ++n) _Pragma("unroll") for (int k = 0; k < 2; ++k) dst[n][k] = *(const PG8_LAS bf16x8*)(lds + PG8_SB(b, h) + boff + n * 2048 + k * 1024); } while (0)
; template <class Epi, class Sched, bool ALIGN_EPI = false, bool SP2 = false>
; __device__ __forceinline__ void gemm_phase(PG8_LAS unsigned char* lds, const Gemm g, const Sched& S, const Epi& E) {
;     ...
;         for (int t = 0; t < nt; t += 2) {
;             if constexpr (Epi::MID) { if (t == nt / 2) E.mid(acc, cur, wr, fr, lds); }
;             const bool last = (t == nt - 2);
;             const char* a1 = cA + (size_t)(t + 1) * kstep;
;             const char* a2 = last ? nA : cA + (size_t)(t + 2) * kstep; const char* b2 = last ? nB : cB + (size_t)(t + 2) * kstep;
;             const char* a3 = a2 + kstep; const char* b3 = b2 + kstep;
;             if (last && has_next) S.a_ready(nxt);
;             if constexpr (SP2) {
;             PG8_LDB(B0, 0, 0); PG8_LDB(B1, 0, 1); PG8_SCHED; PG8_LDA(At, 0, 0); PG8_STAGE(PG8_SA(1, 1), a1 + hstep, voffA);
;             PG8_WAIT_V(8); PG8_WAIT_L(0); PG8_BAR; PG8_MMA(0, 0, At, B0); PG8_MMA(0, 1, At, B1); PG8_BAR; PG8_SCHED;
;             if constexpr (Epi::XPF) {
;             const bool xsel = last && !has_next;
;             const char* xt = (const char*)E.x + ((size_t)cur.pm * BM * 1024 + (size_t)cur.pn * BM) * 4;
;             const unsigned vB[2] = {xsel ? voffX[0] : voffB[0], xsel ? voffX[1] : voffB[1]}, vA[2] = {xsel ? voffX[0] : voffA[0], xsel ? voffX[1] : voffA[1]};
;     ...
;             PG8_LDA(At, 0, 1); PG8_STAGE(PG8_SB(0, 0), xsel ? PG8_XR(0) : b2, vB); PG8_STAGE(PG8_SB(0, 1), xsel ? PG8_XR(1) : b2 + hstep, vB); PG8_STAGE(PG8_SA(0, 0), xsel ? PG8_XR(2) : a2, vA);
;             PG8_WAIT_V(8); PG8_WAIT_L(0); PG8_BAR; PG8_MMA(1, 0, At, B0); PG8_MMA(1, 1, At, B1); PG8_BAR; PG8_SCHED;
.LBB0_515:
	s_add_u32 s73, s24, s26
	s_addc_u32 s74, s25, s27
	s_add_u32 s73, s73, 0x100
	v_add_u32_e32 v151, s41, v131
	s_addc_u32 s76, s74, 0
	ds_read_b128 v[152:155], v151
	ds_read_b128 v[156:159], v151 offset:1024
	ds_read_b128 v[162:165], v151 offset:2048
	ds_read_b128 v[166:169], v151 offset:3072
	v_add_u32_e32 v151, s42, v131
	s_add_u32 s77, s19, s26
	ds_read_b128 v[170:173], v151
	ds_read_b128 v[174:177], v151 offset:1024
	ds_read_b128 v[178:181], v151 offset:2048
	ds_read_b128 v[182:185], v151 offset:3072
	s_addc_u32 s80, s56, s27
	s_cmpk_eq_i32 s26, 0xf00
	s_cselect_b64 s[78:79], -1, 0
	s_and_b64 s[74:75], s[78:79], exec
	s_cselect_b32 s82, s58, s73
	s_cselect_b32 s81, s57, s76
	s_cselect_b32 s75, s59, s77
	s_cselect_b32 s76, s15, s80
	s_add_u32 s73, s82, 0x80
	s_addc_u32 s74, s81, 0
	v_lshl_add_u64 v[218:219], v[142:143], 0, s[26:27]
	s_add_i32 m0, s33, 0xc000
	ds_read_b128 v[186:189], v149
	ds_read_b128 v[190:193], v149 offset:1024
	ds_read_b128 v[194:197], v149 offset:2048
	ds_read_b128 v[198:201], v149 offset:3072
	ds_read_b128 v[202:205], v149 offset:4096
	ds_read_b128 v[206:209], v149 offset:5120
	ds_read_b128 v[210:213], v149 offset:6144
	ds_read_b128 v[214:217], v149 offset:7168
	global_load_lds_dwordx4 v[218:219], off
	v_lshl_add_u64 v[218:219], v[144:145], 0, s[26:27]
	s_add_i32 m0, s33, 0xe000
	s_nop 0
	global_load_lds_dwordx4 v[218:219], off
	s_waitcnt vmcnt(8)
	s_waitcnt lgkmcnt(0)
	s_barrier
	s_setprio 1
	s_waitcnt lgkmcnt(0)
	v_mfma_f32_16x16x32_bf16 v[124:127], v[152:155], v[186:189], v[124:127]
	v_mfma_f32_16x16x32_bf16 v[120:123], v[162:165], v[186:189], v[120:123]
	v_mfma_f32_16x16x32_bf16 v[108:111], v[152:155], v[194:197], v[108:111]
	v_mfma_f32_16x16x32_bf16 v[104:107], v[162:165], v[194:197], v[104:107]
	v_mfma_f32_16x16x32_bf16 v[92:95], v[152:155], v[202:205], v[92:95]
	v_mfma_f32_16x16x32_bf16 v[88:91], v[162:165], v[202:205], v[88:91]
	v_mfma_f32_16x16x32_bf16 v[72:75], v[152:155], v[210:213], v[72:75]
	v_mfma_f32_16x16x32_bf16 v[68:71], v[162:165], v[210:213], v[68:71]
	v_mfma_f32_16x16x32_bf16 v[124:127], v[156:159], v[190:193], v[124:127]
	v_mfma_f32_16x16x32_bf16 v[120:123], v[166:169], v[190:193], v[120:123]
	v_mfma_f32_16x16x32_bf16 v[108:111], v[156:159], v[198:201], v[108:111]
	v_mfma_f32_16x16x32_bf16 v[104:107], v[166:169], v[198:201], v[104:107]
	v_mfma_f32_16x16x32_bf16 v[92:95], v[156:159], v[206:209], v[92:95]
	v_mfma_f32_16x16x32_bf16 v[88:91], v[166:169], v[206:209], v[88:91]
	v_mfma_f32_16x16x32_bf16 v[72:75], v[156:159], v[214:217], v[72:75]
	v_mfma_f32_16x16x32_bf16 v[68:71], v[166:169], v[214:217], v[68:71]
	s_setprio 0
	s_setprio 1
	v_mfma_f32_16x16x32_bf16 v[116:119], v[170:173], v[186:189], v[116:119]
	v_mfma_f32_16x16x32_bf16 v[112:115], v[178:181], v[186:189], v[112:115]
	v_mfma_f32_16x16x32_bf16 v[100:103], v[170:173], v[194:197], v[100:103]
	v_mfma_f32_16x16x32_bf16 v[96:99], v[178:181], v[194:197], v[96:99]
	v_mfma_f32_16x16x32_bf16 v[84:87], v[170:173], v[202:205], v[84:87]
	v_mfma_f32_16x16x32_bf16 v[76:79], v[178:181], v[202:205], v[76:79]
	v_mfma_f32_16x16x32_bf16 v[64:67], v[170:173], v[210:213], v[64:67]
	v_mfma_f32_16x16x32_bf16 v[60:63], v[178:181], v[210:213], v[60:63]
	v_mfma_f32_16x16x32_bf16 v[116:119], v[174:177], v[190:193], v[116:119]
	v_mfma_f32_16x16x32_bf16 v[112:115], v[182:185], v[190:193], v[112:115]
	v_mfma_f32_16x16x32_bf16 v[100:103], v[174:177], v[198:201], v[100:103]
	v_mfma_f32_16x16x32_bf16 v[96:99], v[182:185], v[198:201], v[96:99]
	v_mfma_f32_16x16x32_bf16 v[84:87], v[174:177], v[206:209], v[84:87]
	v_mfma_f32_16x16x32_bf16 v[76:79], v[182:185], v[206:209], v[76:79]
	v_mfma_f32_16x16x32_bf16 v[64:67], v[174:177], v[214:217], v[64:67]
	v_mfma_f32_16x16x32_bf16 v[60:63], v[182:185], v[214:217], v[60:63]
	s_setprio 0
	s_barrier
	s_and_b64 vcc, s[4:5], s[78:79]
	s_and_b64 s[78:79], vcc, exec
	s_cselect_b32 s79, s3, s76
	s_cselect_b32 s78, s1, s75
	s_add_i32 s77, s41, s31
	v_cndmask_b32_e32 v151, v128, v146, vcc
	s_mov_b32 m0, s77
	ds_read_b128 v[186:189], v149 offset:16384
	ds_read_b128 v[190:193], v149 offset:17408
	ds_read_b128 v[194:197], v149 offset:18432
	ds_read_b128 v[198:201], v149 offset:19456
	ds_read_b128 v[202:205], v149 offset:20480
	ds_read_b128 v[206:209], v149 offset:21504
	ds_read_b128 v[210:213], v149 offset:22528
	ds_read_b128 v[214:217], v149 offset:23552
	global_load_lds_dwordx4 v151, s[78:79]
	s_add_i32 m0, s77, 0x2000
	s_add_u32 s77, s75, 0x80000
	v_cndmask_b32_e32 v161, v130, v147, vcc
	s_addc_u32 s80, s76, 0
	global_load_lds_dwordx4 v161, s[78:79]
	s_and_b64 s[78:79], vcc, exec
	s_cselect_b32 s79, s61, s80
	s_cselect_b32 s78, s60, s77
	s_add_i32 s77, s42, s31
	s_mov_b32 m0, s77
	s_nop 0
	global_load_lds_dwordx4 v151, s[78:79]
	s_add_i32 m0, s77, 0x2000
	s_nop 0
	global_load_lds_dwordx4 v161, s[78:79]
	s_and_b64 s[78:79], vcc, exec
	s_cselect_b32 s79, s63, s81
	s_cselect_b32 s78, s62, s82
	s_mov_b32 m0, s33
	s_nop 0
	global_load_lds_dwordx4 v151, s[78:79]
	s_mov_b32 m0, s34
	s_nop 0
	global_load_lds_dwordx4 v161, s[78:79]
	s_waitcnt vmcnt(8)
	s_waitcnt lgkmcnt(0)
	s_barrier
; #define PG8_STAGE(bufoff, gbase, voff) do { _Pragma("unroll") for (int _i = 0; _i < 2; ++_i) \
;         __builtin_amdgcn_global_load_lds((const unsigned*)((const char*)(gbase) + (voff)[_i]), (PG8_LAS unsigned*)(lds + (bufoff) + ldsw + _i * 8192), 16, 0, 0); } while (0)
; #define PG8_LDA(dst, b, h) do { _Pragma("unroll") for (int m = 0; m < 4; ++m) _Pragma("unroll") for (int k = 0; k < 2; ++k) dst[m][k] = *(const PG8_LAS bf16x8*)(lds + PG8_SA(b, h) + aoff + m * 2048 + k * 1024); } while (0)
; #define PG8_LDB(dst, b, h) do { _Pragma("unroll") for (int n = 0; n < 2; ++n) _Pragma("unroll") for (int k = 0; k < 2; ++k) dst[n][k] = *(const PG8_LAS bf16x8*)(lds + PG8_SB(b, h) + boff + n * 2048 + k * 1024); } while (0)
; #define PG8_MMA(ai, bj, At, Bt) do { __builtin_amdgcn_s_setprio(1); _Pragma("unroll") for (int m = 0; m < 4; ++m) _Pragma("unroll") for (int n = 0; n < 2; ++n) _Pragma("unroll") for (int k = 0; k < 2; ++k) \
;         acc[ai][bj][m][n] = __builtin_amdgcn_mfma_f32_16x16x32_bf16(Bt[n][k], At[m][k], acc[ai][bj][m][n], 0, 0, 0); __builtin_amdgcn_s_setprio(0); } while (0)
; #define PG8_WAIT_V(n) asm volatile("s_waitcnt vmcnt(" #n ")" ::: "memory")
; #define PG8_WAIT_L(n) asm volatile("s_waitcnt lgkmcnt(" #n ")" ::: "memory")
; #define PG8_BAR __builtin_amdgcn_s_barrier()
; #define PG8_SCHED __builtin_amdgcn_sched_barrier(0)
; template <class Epi, class Sched, bool ALIGN_EPI = false, bool SP2 = false>
; __device__ __forceinline__ void gemm_phase(PG8_LAS unsigned char* lds, const Gemm g, const Sched& S, const Epi& E) {
;     ...
;             PG8_WAIT_V(8); PG8_WAIT_L(0); PG8_BAR; PG8_MMA(1, 0, At, B0); PG8_MMA(1, 1, At, B1); PG8_BAR; PG8_SCHED;
;             PG8_LDB(B0, 1, 0); PG8_LDB(B1, 1, 1); PG8_SCHED; PG8_LDA(At, 1, 0); PG8_STAGE(PG8_SA(0, 1), xsel ? PG8_XR(3) : a2 + hstep, vA);
;             PG8_WAIT_V(8); PG8_WAIT_L(0); PG8_BAR; PG8_MMA(0, 0, At, B0); PG8_MMA(0, 1, At, B1); PG8_BAR; PG8_SCHED;
;             PG8_LDA(At, 1, 1); PG8_STAGE(PG8_SB(1, 0), xsel ? PG8_XR(4) : b3, vB); PG8_STAGE(PG8_SB(1, 1), xsel ? PG8_XR(5) : b3 + hstep, vB); PG8_STAGE(PG8_SA(1, 0), xsel ? PG8_XR(6) : a3, vA);
	s_setprio 1
	s_waitcnt lgkmcnt(0)
	v_mfma_f32_16x16x32_bf16 v[56:59], v[152:155], v[186:189], v[56:59]
	v_mfma_f32_16x16x32_bf16 v[52:55], v[162:165], v[186:189], v[52:55]
	v_mfma_f32_16x16x32_bf16 v[40:43], v[152:155], v[194:197], v[40:43]
	v_mfma_f32_16x16x32_bf16 v[36:39], v[162:165], v[194:197], v[36:39]
	v_mfma_f32_16x16x32_bf16 v[24:27], v[152:155], v[202:205], v[24:27]
	v_mfma_f32_16x16x32_bf16 v[20:23], v[162:165], v[202:205], v[20:23]
	v_mfma_f32_16x16x32_bf16 v[4:7], v[152:155], v[210:213], v[4:7]
	v_mfma_f32_16x16x32_bf16 v[0:3], v[162:165], v[210:213], v[0:3]
	v_mfma_f32_16x16x32_bf16 v[56:59], v[156:159], v[190:193], v[56:59]
	v_mfma_f32_16x16x32_bf16 v[52:55], v[166:169], v[190:193], v[52:55]
	v_mfma_f32_16x16x32_bf16 v[40:43], v[156:159], v[198:201], v[40:43]
	v_mfma_f32_16x16x32_bf16 v[36:39], v[166:169], v[198:201], v[36:39]
	v_mfma_f32_16x16x32_bf16 v[24:27], v[156:159], v[206:209], v[24:27]
	v_mfma_f32_16x16x32_bf16 v[20:23], v[166:169], v[206:209], v[20:23]
	v_mfma_f32_16x16x32_bf16 v[4:7], v[156:159], v[214:217], v[4:7]
	v_mfma_f32_16x16x32_bf16 v[0:3], v[166:169], v[214:217], v[0:3]
	s_setprio 0
	s_setprio 1
	v_mfma_f32_16x16x32_bf16 v[48:51], v[170:173], v[186:189], v[48:51]
	v_mfma_f32_16x16x32_bf16 v[44:47], v[178:181], v[186:189], v[44:47]
	v_mfma_f32_16x16x32_bf16 v[32:35], v[170:173], v[194:197], v[32:35]
	v_mfma_f32_16x16x32_bf16 v[28:31], v[178:181], v[194:197], v[28:31]
	v_mfma_f32_16x16x32_bf16 v[8:11], v[170:173], v[202:205], v[8:11]
	v_mfma_f32_16x16x32_bf16 v[80:83], v[178:181], v[202:205], v[80:83]
	v_mfma_f32_16x16x32_bf16 v[16:19], v[170:173], v[210:213], v[16:19]
	v_mfma_f32_16x16x32_bf16 v[12:15], v[178:181], v[210:213], v[12:15]
	v_mfma_f32_16x16x32_bf16 v[48:51], v[174:177], v[190:193], v[48:51]
	v_mfma_f32_16x16x32_bf16 v[44:47], v[182:185], v[190:193], v[44:47]
	v_mfma_f32_16x16x32_bf16 v[32:35], v[174:177], v[198:201], v[32:35]
	v_mfma_f32_16x16x32_bf16 v[28:31], v[182:185], v[198:201], v[28:31]
	v_mfma_f32_16x16x32_bf16 v[8:11], v[174:177], v[206:209], v[8:11]
	v_mfma_f32_16x16x32_bf16 v[80:83], v[182:185], v[206:209], v[80:83]
	v_mfma_f32_16x16x32_bf16 v[16:19], v[174:177], v[214:217], v[16:19]
	v_mfma_f32_16x16x32_bf16 v[12:15], v[182:185], v[214:217], v[12:15]
	s_setprio 0
	s_barrier
	s_add_i32 s77, 0, 0x18000
	s_add_i32 s80, 0, 0x1c000
	v_add_u32_e32 v166, s77, v131
	v_add_u32_e32 v182, s80, v131
	ds_read_b128 v[152:155], v166
	ds_read_b128 v[156:159], v166 offset:1024
	ds_read_b128 v[162:165], v166 offset:2048
	ds_read_b128 v[166:169], v166 offset:3072
	ds_read_b128 v[170:173], v182
	ds_read_b128 v[174:177], v182 offset:1024
	ds_read_b128 v[178:181], v182 offset:2048
	ds_read_b128 v[182:185], v182 offset:3072
	s_add_u32 s82, s82, 0x80000
	s_addc_u32 s81, s81, 0
	s_and_b64 s[78:79], vcc, exec
	s_cselect_b32 s79, s65, s81
	s_cselect_b32 s78, s64, s82
	s_mov_b32 m0, s35
	ds_read_b128 v[186:189], v149 offset:32768
	ds_read_b128 v[190:193], v149 offset:33792
	ds_read_b128 v[194:197], v149 offset:34816
	ds_read_b128 v[198:201], v149 offset:35840
	ds_read_b128 v[202:205], v149 offset:36864
	ds_read_b128 v[206:209], v149 offset:37888
	ds_read_b128 v[210:213], v149 offset:38912
	ds_read_b128 v[214:217], v149 offset:39936
	global_load_lds_dwordx4 v151, s[78:79]
	s_mov_b32 m0, s36
	s_nop 0
	global_load_lds_dwordx4 v161, s[78:79]
	s_waitcnt vmcnt(8)
	s_waitcnt lgkmcnt(0)
	s_barrier
	s_setprio 1
	s_waitcnt lgkmcnt(0)
	v_mfma_f32_16x16x32_bf16 v[124:127], v[152:155], v[186:189], v[124:127]
	v_mfma_f32_16x16x32_bf16 v[120:123], v[162:165], v[186:189], v[120:123]
	v_mfma_f32_16x16x32_bf16 v[108:111], v[152:155], v[194:197], v[108:111]
	v_mfma_f32_16x16x32_bf16 v[104:107], v[162:165], v[194:197], v[104:107]
	v_mfma_f32_16x16x32_bf16 v[92:95], v[152:155], v[202:205], v[92:95]
	v_mfma_f32_16x16x32_bf16 v[88:91], v[162:165], v[202:205], v[88:91]
	v_mfma_f32_16x16x32_bf16 v[72:75], v[152:155], v[210:213], v[72:75]
	v_mfma_f32_16x16x32_bf16 v[68:71], v[162:165], v[210:213], v[68:71]
	v_mfma_f32_16x16x32_bf16 v[124:127], v[156:159], v[190:193], v[124:127]
	v_mfma_f32_16x16x32_bf16 v[120:123], v[166:169], v[190:193], v[120:123]
	v_mfma_f32_16x16x32_bf16 v[108:111], v[156:159], v[198:201], v[108:111]
	v_mfma_f32_16x16x32_bf16 v[104:107], v[166:169], v[198:201], v[104:107]
	v_mfma_f32_16x16x32_bf16 v[92:95], v[156:159], v[206:209], v[92:95]
	v_mfma_f32_16x16x32_bf16 v[88:91], v[166:169], v[206:209], v[88:91]
	v_mfma_f32_16x16x32_bf16 v[72:75], v[156:159], v[214:217], v[72:75]
	v_mfma_f32_16x16x32_bf16 v[68:71], v[166:169], v[214:217], v[68:71]
	s_setprio 0
	s_setprio 1
	v_mfma_f32_16x16x32_bf16 v[116:119], v[170:173], v[186:189], v[116:119]
	v_mfma_f32_16x16x32_bf16 v[112:115], v[178:181], v[186:189], v[112:115]
	v_mfma_f32_16x16x32_bf16 v[100:103], v[170:173], v[194:197], v[100:103]
	v_mfma_f32_16x16x32_bf16 v[96:99], v[178:181], v[194:197], v[96:99]
	v_mfma_f32_16x16x32_bf16 v[84:87], v[170:173], v[202:205], v[84:87]
	v_mfma_f32_16x16x32_bf16 v[76:79], v[178:181], v[202:205], v[76:79]
	v_mfma_f32_16x16x32_bf16 v[64:67], v[170:173], v[210:213], v[64:67]
	v_mfma_f32_16x16x32_bf16 v[60:63], v[178:181], v[210:213], v[60:63]
	v_mfma_f32_16x16x32_bf16 v[116:119], v[174:177], v[190:193], v[116:119]
	v_mfma_f32_16x16x32_bf16 v[112:115], v[182:185], v[190:193], v[112:115]
	v_mfma_f32_16x16x32_bf16 v[100:103], v[174:177], v[198:201], v[100:103]
	v_mfma_f32_16x16x32_bf16 v[96:99], v[182:185], v[198:201], v[96:99]
	v_mfma_f32_16x16x32_bf16 v[84:87], v[174:177], v[206:209], v[84:87]
	v_mfma_f32_16x16x32_bf16 v[76:79], v[182:185], v[206:209], v[76:79]
	v_mfma_f32_16x16x32_bf16 v[64:67], v[174:177], v[214:217], v[64:67]
	v_mfma_f32_16x16x32_bf16 v[60:63], v[182:185], v[214:217], v[60:63]
	s_setprio 0
	s_barrier
; #define PG8_STAGE(bufoff, gbase, voff) do { _Pragma("unroll") for (int _i = 0; _i < 2; ++_i) \
;         __builtin_amdgcn_global_load_lds((const unsigned*)((const char*)(gbase) + (voff)[_i]), (PG8_LAS unsigned*)(lds + (bufoff) + ldsw + _i * 8192), 16, 0, 0); } while (0)
; #define PG8_LDA(dst, b, h) do { _Pragma("unroll") for (int m = 0; m < 4; ++m) _Pragma("unroll") for (int k = 0; k < 2; ++k) dst[m][k] = *(const PG8_LAS bf16x8*)(lds + PG8_SA(b, h) + aoff + m * 2048 + k * 1024); } while (0)
; #define PG8_MMA(ai, bj, At, Bt) do { __builtin_amdgcn_s_setprio(1); _Pragma("unroll") for (int m = 0; m < 4; ++m) _Pragma("unroll") for (int n = 0; n < 2; ++n) _Pragma("unroll") for (int k = 0; k < 2; ++k) \
;         acc[ai][bj][m][n] = __builtin_amdgcn_mfma_f32_16x16x32_bf16(Bt[n][k], At[m][k], acc[ai][bj][m][n], 0, 0, 0); __builtin_amdgcn_s_setprio(0); } while (0)
; #define PG8_WAIT_V(n) asm volatile("s_waitcnt vmcnt(" #n ")" ::: "memory")
; #define PG8_WAIT_L(n) asm volatile("s_waitcnt lgkmcnt(" #n ")" ::: "memory")
; #define PG8_BAR __builtin_amdgcn_s_barrier()
; #define PG8_SCHED __builtin_amdgcn_sched_barrier(0)
; template <class Epi, class Sched, bool ALIGN_EPI = false, bool SP2 = false>
; __device__ __forceinline__ void gemm_phase(PG8_LAS unsigned char* lds, const Gemm g, const Sched& S, const Epi& E) {
;     ...
;         for (int t = 0; t < nt; t += 2) {
;     ...
;             PG8_LDA(At, 1, 1); PG8_STAGE(PG8_SB(1, 0), xsel ? PG8_XR(4) : b3, vB); PG8_STAGE(PG8_SB(1, 1), xsel ? PG8_XR(5) : b3 + hstep, vB); PG8_STAGE(PG8_SA(1, 0), xsel ? PG8_XR(6) : a3, vA);
;             PG8_WAIT_V(8); PG8_WAIT_L(0); PG8_BAR; PG8_MMA(1, 0, At, B0); PG8_MMA(1, 1, At, B1); PG8_BAR; PG8_SCHED;
	s_add_u32 s81, s75, 0x80
	s_addc_u32 s82, s76, 0
	s_and_b64 s[78:79], vcc, exec
	s_cselect_b32 s79, s67, s82
	s_cselect_b32 s78, s66, s81
	s_add_i32 s77, s77, s31
	s_mov_b32 m0, s77
	ds_read_b128 v[186:189], v149 offset:49152
	ds_read_b128 v[190:193], v149 offset:50176
	ds_read_b128 v[194:197], v149 offset:51200
	ds_read_b128 v[198:201], v149 offset:52224
	ds_read_b128 v[202:205], v149 offset:53248
	ds_read_b128 v[206:209], v149 offset:54272
	ds_read_b128 v[210:213], v149 offset:55296
	ds_read_b128 v[214:217], v149 offset:56320
	global_load_lds_dwordx4 v151, s[78:79]
	s_add_i32 m0, s77, 0x2000
	s_add_u32 s75, s75, 0x80080
	global_load_lds_dwordx4 v161, s[78:79]
	s_addc_u32 s78, s76, 0
	s_and_b64 s[76:77], vcc, exec
	s_cselect_b32 s77, s69, s78
	s_cselect_b32 s76, s68, s75
	s_add_i32 s75, s80, s31
	s_mov_b32 m0, s75
	s_nop 0
	global_load_lds_dwordx4 v151, s[76:77]
	s_add_i32 m0, s75, 0x2000
	s_nop 0
	global_load_lds_dwordx4 v161, s[76:77]
	s_and_b64 s[76:77], vcc, exec
	s_cselect_b32 s75, s71, s74
	s_cselect_b32 s74, s70, s73
	s_mov_b32 m0, s37
	s_nop 0
	global_load_lds_dwordx4 v151, s[74:75]
	s_mov_b32 m0, s38
	s_nop 0
	global_load_lds_dwordx4 v161, s[74:75]
	s_waitcnt vmcnt(8)
	s_waitcnt lgkmcnt(0)
	s_barrier
	s_setprio 1
	s_waitcnt lgkmcnt(0)
	v_mfma_f32_16x16x32_bf16 v[56:59], v[152:155], v[186:189], v[56:59]
	v_mfma_f32_16x16x32_bf16 v[52:55], v[162:165], v[186:189], v[52:55]
	v_mfma_f32_16x16x32_bf16 v[40:43], v[152:155], v[194:197], v[40:43]
	v_mfma_f32_16x16x32_bf16 v[36:39], v[162:165], v[194:197], v[36:39]
	v_mfma_f32_16x16x32_bf16 v[24:27], v[152:155], v[202:205], v[24:27]
	v_mfma_f32_16x16x32_bf16 v[20:23], v[162:165], v[202:205], v[20:23]
	v_mfma_f32_16x16x32_bf16 v[4:7], v[152:155], v[210:213], v[4:7]
	v_mfma_f32_16x16x32_bf16 v[0:3], v[162:165], v[210:213], v[0:3]
	v_mfma_f32_16x16x32_bf16 v[56:59], v[156:159], v[190:193], v[56:59]
	v_mfma_f32_16x16x32_bf16 v[52:55], v[166:169], v[190:193], v[52:55]
	v_mfma_f32_16x16x32_bf16 v[40:43], v[156:159], v[198:201], v[40:43]
	v_mfma_f32_16x16x32_bf16 v[36:39], v[166:169], v[198:201], v[36:39]
	v_mfma_f32_16x16x32_bf16 v[24:27], v[156:159], v[206:209], v[24:27]
	v_mfma_f32_16x16x32_bf16 v[20:23], v[166:169], v[206:209], v[20:23]
	v_mfma_f32_16x16x32_bf16 v[4:7], v[156:159], v[214:217], v[4:7]
	v_mfma_f32_16x16x32_bf16 v[0:3], v[166:169], v[214:217], v[0:3]
	s_setprio 0
	s_setprio 1
	v_mfma_f32_16x16x32_bf16 v[48:51], v[170:173], v[186:189], v[48:51]
	v_mfma_f32_16x16x32_bf16 v[44:47], v[178:181], v[186:189], v[44:47]
	v_mfma_f32_16x16x32_bf16 v[32:35], v[170:173], v[194:197], v[32:35]
	v_mfma_f32_16x16x32_bf16 v[28:31], v[178:181], v[194:197], v[28:31]
	v_mfma_f32_16x16x32_bf16 v[8:11], v[170:173], v[202:205], v[8:11]
	v_mfma_f32_16x16x32_bf16 v[80:83], v[178:181], v[202:205], v[80:83]
	v_mfma_f32_16x16x32_bf16 v[16:19], v[170:173], v[210:213], v[16:19]
	v_mfma_f32_16x16x32_bf16 v[12:15], v[178:181], v[210:213], v[12:15]
	s_add_i32 s72, s72, 2
	s_add_u32 s26, s26, 0x100
	s_addc_u32 s27, s27, 0
	s_cmp_gt_u32 s72, 29
	v_mfma_f32_16x16x32_bf16 v[48:51], v[174:177], v[190:193], v[48:51]
	v_mfma_f32_16x16x32_bf16 v[44:47], v[182:185], v[190:193], v[44:47]
	v_mfma_f32_16x16x32_bf16 v[32:35], v[174:177], v[198:201], v[32:35]
	v_mfma_f32_16x16x32_bf16 v[28:31], v[182:185], v[198:201], v[28:31]
	v_mfma_f32_16x16x32_bf16 v[8:11], v[174:177], v[206:209], v[8:11]
	v_mfma_f32_16x16x32_bf16 v[80:83], v[182:185], v[206:209], v[80:83]
	v_mfma_f32_16x16x32_bf16 v[16:19], v[174:177], v[214:217], v[16:19]
	v_mfma_f32_16x16x32_bf16 v[12:15], v[182:185], v[214:217], v[12:15]
	s_setprio 0
	s_barrier
	s_cbranch_scc1 .LBB0_518
